# pool_tile output: 16 global_store_short per group replaced by LDS-staged 2x dwordx4 stores; + no entry grid.sync
# baseline (speedup 1.0000x reference)
; __device__ __forceinline__ void pool_tile(const Ctx& c, int l, int tile) {
;     ...
;             f32x16 acc = {};
; #pragma unroll 8
;             for (int s = 0; s < 32; ++s) {
;                 const float a = Pm[(32 * rt + li) * 65 + 2 * s + lh];
;                 const float b = pw[(size_t)(2 * s + lh) * 64];
;                 acc = __builtin_amdgcn_mfma_f32_32x32x2f32(a, b, acc, 0, 0, 0);
;             }
.LBB0_353:
	v_lshl_add_u64 v[144:145], v[110:111], 0, s[68:69]
	global_load_dword v113, v[144:145], off
	global_load_dword v148, v[144:145], off offset:512
	global_load_dword v149, v[144:145], off offset:1024
	global_load_dword v150, v[144:145], off offset:1536
	global_load_dword v151, v[144:145], off offset:2048
	ds_read2_b32 v[146:147], v112 offset1:2
	global_load_dword v152, v[144:145], off offset:2560
	global_load_dword v153, v[144:145], off offset:3072
	global_load_dword v154, v[144:145], off offset:3584
	ds_read2_b32 v[144:145], v112 offset0:4 offset1:6
	s_add_u32 s68, s68, 0x1000
	s_addc_u32 s69, s69, 0
	s_cmpk_eq_i32 s68, 0x4000
	s_waitcnt vmcnt(7) lgkmcnt(1)
	v_mfma_f32_32x32x2_f32 v[0:15], v146, v113, v[0:15]
	s_waitcnt vmcnt(6)
	v_mfma_f32_32x32x2_f32 v[0:15], v147, v148, v[0:15]
	s_waitcnt vmcnt(5) lgkmcnt(0)
	v_mfma_f32_32x32x2_f32 v[0:15], v144, v149, v[0:15]
	s_waitcnt vmcnt(4)
	v_mfma_f32_32x32x2_f32 v[0:15], v145, v150, v[0:15]
	ds_read2_b32 v[144:145], v112 offset0:8 offset1:10
	s_waitcnt vmcnt(3) lgkmcnt(0)
	v_mfma_f32_32x32x2_f32 v[0:15], v144, v151, v[0:15]
	s_waitcnt vmcnt(2)
	v_mfma_f32_32x32x2_f32 v[0:15], v145, v152, v[0:15]
	ds_read2_b32 v[144:145], v112 offset0:12 offset1:14
	v_add_u32_e32 v112, 64, v112
	s_waitcnt vmcnt(1) lgkmcnt(0)
	v_mfma_f32_32x32x2_f32 v[0:15], v144, v153, v[0:15]
	s_waitcnt vmcnt(0)
	v_mfma_f32_32x32x2_f32 v[0:15], v145, v154, v[0:15]
	s_cbranch_scc0 .LBB0_353
; __device__ __forceinline__ float silu_f(float v) { return v * __builtin_amdgcn_rcpf(1.0f + __builtin_amdgcn_exp2f(-1.4426950408889634f * v)); }
; __device__ __forceinline__ unsigned pk_bf16(float lo, float hi) { return pg8::cvt_pk_bf16(lo, hi); }
; __device__ __forceinline__ void pool_tile(const Ctx& c, int l, int tile) {
;     ...
; #pragma unroll
;             for (int r = 0; r < 16; ++r) {
;                 const int i = (r & 3) + 8 * (r >> 2) + 4 * lh; const size_t tok = (size_t)(t0 + 32 * rt + i);
;                 const float v = acc[r] * sc * silu_f(__uint_as_float((unsigned)gv[r] << 16));
;                 Y[tok * 1024 + gi * 64 + j] = (bf16_t)(pk_bf16(v, 0.f) & 0xffffu);
;             }
	v_lshlrev_b32_e32 v143, 16, v143
	v_mul_f32_e32 v144, 0xbfb8aa3b, v143
	v_exp_f32_e32 v144, v144
	s_lshl_b32 s34, s16, 1
	s_nop 12
	v_mul_f32_e32 v0, v129, v0
	v_lshl_add_u64 v[112:113], v[34:35], 0, s[34:35]
	v_and_b32_e32 v160, 31, v212
	v_lshlrev_b32_e32 v160, 1, v160
	v_and_b32_e32 v161, 32, v212
	v_lshl_or_b32 v160, v161, 3, v160
	v_and_b32_e32 v161, 0x1c0, v212
	v_lshlrev_b32_e32 v161, 5, v161
	v_or_b32_e32 v160, v160, v161
	v_add_u32_e32 v160, 0x18000, v160
	v_and_b32_e32 v162, 63, v212
	v_lshl_or_b32 v162, v162, 4, v161
	v_add_u32_e32 v162, 0x18000, v162
	v_and_b32_e32 v164, 0x3c, v212
	v_lshlrev_b32_e32 v164, 9, v164
	v_and_b32_e32 v163, 32, v212
	v_lshlrev_b32_e32 v163, 8, v163
	v_sub_u32_e32 v164, v164, v163
	v_and_b32_e32 v163, 3, v212
	v_lshl_add_u32 v164, v163, 4, v164
	v_and_b32_e32 v163, 31, v212
	v_lshlrev_b32_e32 v163, 1, v163
	v_sub_u32_e32 v164, v164, v163
	v_ashrrev_i32_e32 v165, 31, v164
	v_lshl_add_u64 v[166:167], v[112:113], 0, v[76:77]
	v_lshl_add_u64 v[166:167], v[166:167], 0, v[164:165]
	v_lshl_add_u64 v[168:169], v[166:167], 0, s[96:97]
	v_lshl_add_u64 v[168:169], v[168:169], 0, s[96:97]
	v_add_f32_e32 v144, 1.0, v144
	v_rcp_f32_e32 v144, v144
	s_add_i32 s13, s13, 1
	v_lshl_add_u64 v[110:111], v[110:111], 0, s[96:97]
	s_cmp_eq_u32 s13, 4
	v_mul_f32_e32 v143, v144, v143
	v_mul_f32_e32 v0, v143, v0
	v_cvt_pk_bf16_f32 v0, v0, s0
	ds_write_b16 v160, v0
	v_mul_f32_e32 v0, v129, v1
	v_lshlrev_b32_e32 v1, 16, v142
	v_mul_f32_e32 v142, 0xbfb8aa3b, v1
	v_exp_f32_e32 v142, v142
	s_nop 0
	v_add_f32_e32 v142, 1.0, v142
	v_rcp_f32_e32 v142, v142
	s_nop 0
	v_mul_f32_e32 v1, v142, v1
	v_mul_f32_e32 v0, v1, v0
	v_cvt_pk_bf16_f32 v142, v0, s0
	ds_write_b16 v160, v142 offset:64
	v_lshlrev_b32_e32 v1, 16, v141
	v_mul_f32_e32 v0, v129, v2
	v_mul_f32_e32 v2, 0xbfb8aa3b, v1
	v_exp_f32_e32 v2, v2
	s_nop 0
	v_add_f32_e32 v2, 1.0, v2
	v_rcp_f32_e32 v2, v2
	s_nop 0
	v_mul_f32_e32 v1, v2, v1
	v_mul_f32_e32 v0, v1, v0
	v_cvt_pk_bf16_f32 v2, v0, s0
	ds_write_b16 v160, v2 offset:128
	v_lshlrev_b32_e32 v1, 16, v140
	v_mul_f32_e32 v2, 0xbfb8aa3b, v1
	v_exp_f32_e32 v2, v2
	v_mul_f32_e32 v0, v129, v3
	v_add_f32_e32 v2, 1.0, v2
	v_rcp_f32_e32 v2, v2
	s_nop 0
	v_mul_f32_e32 v1, v2, v1
	v_mul_f32_e32 v0, v1, v0
	v_cvt_pk_bf16_f32 v2, v0, s0
	ds_write_b16 v160, v2 offset:192
	v_lshlrev_b32_e32 v1, 16, v139
	v_mul_f32_e32 v2, 0xbfb8aa3b, v1
	v_exp_f32_e32 v2, v2
	v_mul_f32_e32 v0, v129, v4
	v_add_f32_e32 v2, 1.0, v2
	v_rcp_f32_e32 v2, v2
	s_nop 0
	v_mul_f32_e32 v1, v2, v1
	v_mul_f32_e32 v0, v1, v0
	v_cvt_pk_bf16_f32 v2, v0, s0
	ds_write_b16 v160, v2 offset:512
	v_lshlrev_b32_e32 v1, 16, v138
	v_mul_f32_e32 v2, 0xbfb8aa3b, v1
	v_exp_f32_e32 v2, v2
	v_mul_f32_e32 v0, v129, v5
	v_add_f32_e32 v2, 1.0, v2
	v_rcp_f32_e32 v2, v2
	s_nop 0
	v_mul_f32_e32 v1, v2, v1
	v_mul_f32_e32 v0, v1, v0
	v_cvt_pk_bf16_f32 v2, v0, s0
	ds_write_b16 v160, v2 offset:576
	v_lshlrev_b32_e32 v1, 16, v137
	v_mul_f32_e32 v2, 0xbfb8aa3b, v1
	v_exp_f32_e32 v2, v2
	v_mul_f32_e32 v0, v129, v6
	v_add_f32_e32 v2, 1.0, v2
	v_rcp_f32_e32 v2, v2
	s_nop 0
	v_mul_f32_e32 v1, v2, v1
	v_mul_f32_e32 v0, v1, v0
	v_cvt_pk_bf16_f32 v2, v0, s0
	ds_write_b16 v160, v2 offset:640
	v_lshlrev_b32_e32 v1, 16, v136
	v_mul_f32_e32 v2, 0xbfb8aa3b, v1
	v_exp_f32_e32 v2, v2
	v_mul_f32_e32 v0, v129, v7
	v_add_f32_e32 v2, 1.0, v2
	v_rcp_f32_e32 v2, v2
	s_nop 0
	v_mul_f32_e32 v1, v2, v1
	v_mul_f32_e32 v0, v1, v0
	v_cvt_pk_bf16_f32 v2, v0, s0
	ds_write_b16 v160, v2 offset:704
	v_lshlrev_b32_e32 v1, 16, v135
	v_mul_f32_e32 v2, 0xbfb8aa3b, v1
	v_exp_f32_e32 v2, v2
	v_mul_f32_e32 v0, v129, v8
	v_add_f32_e32 v2, 1.0, v2
	v_rcp_f32_e32 v2, v2
	s_nop 0
	v_mul_f32_e32 v1, v2, v1
	v_mul_f32_e32 v0, v1, v0
	v_cvt_pk_bf16_f32 v2, v0, s0
	ds_write_b16 v160, v2 offset:1024
	v_lshlrev_b32_e32 v1, 16, v134
	v_mul_f32_e32 v2, 0xbfb8aa3b, v1
	v_exp_f32_e32 v2, v2
	v_mul_f32_e32 v0, v129, v9
	v_add_f32_e32 v2, 1.0, v2
	v_rcp_f32_e32 v2, v2
	s_nop 0
	v_mul_f32_e32 v1, v2, v1
	v_mul_f32_e32 v0, v1, v0
	v_cvt_pk_bf16_f32 v2, v0, s0
	ds_write_b16 v160, v2 offset:1088
	v_lshlrev_b32_e32 v1, 16, v133
	v_mul_f32_e32 v2, 0xbfb8aa3b, v1
	v_exp_f32_e32 v2, v2
	v_mul_f32_e32 v0, v129, v10
	v_add_f32_e32 v2, 1.0, v2
	v_rcp_f32_e32 v2, v2
	s_nop 0
	v_mul_f32_e32 v1, v2, v1
	v_mul_f32_e32 v0, v1, v0
	v_cvt_pk_bf16_f32 v2, v0, s0
	ds_write_b16 v160, v2 offset:1152
	v_lshlrev_b32_e32 v1, 16, v132
	v_mul_f32_e32 v2, 0xbfb8aa3b, v1
	v_exp_f32_e32 v2, v2
	v_mul_f32_e32 v0, v129, v11
	v_add_f32_e32 v2, 1.0, v2
	v_rcp_f32_e32 v2, v2
	s_nop 0
	v_mul_f32_e32 v1, v2, v1
	v_mul_f32_e32 v0, v1, v0
	v_cvt_pk_bf16_f32 v2, v0, s0
	ds_write_b16 v160, v2 offset:1216
	v_lshlrev_b32_e32 v1, 16, v131
	v_mul_f32_e32 v2, 0xbfb8aa3b, v1
	v_exp_f32_e32 v2, v2
	v_mul_f32_e32 v0, v129, v12
	v_add_f32_e32 v2, 1.0, v2
	v_rcp_f32_e32 v2, v2
	s_nop 0
	v_mul_f32_e32 v1, v2, v1
	v_mul_f32_e32 v0, v1, v0
	v_cvt_pk_bf16_f32 v2, v0, s0
	ds_write_b16 v160, v2 offset:1536
	v_lshlrev_b32_e32 v1, 16, v130
	v_mul_f32_e32 v2, 0xbfb8aa3b, v1
	v_exp_f32_e32 v2, v2
	v_mul_f32_e32 v0, v129, v13
	v_add_f32_e32 v2, 1.0, v2
	v_rcp_f32_e32 v2, v2
	s_nop 0
	v_mul_f32_e32 v1, v2, v1
	v_mul_f32_e32 v0, v1, v0
	v_cvt_pk_bf16_f32 v2, v0, s0
	ds_write_b16 v160, v2 offset:1600
	v_lshlrev_b32_e32 v1, 16, v128
	v_mul_f32_e32 v2, 0xbfb8aa3b, v1
	v_exp_f32_e32 v2, v2
	v_mul_f32_e32 v0, v129, v14
	v_add_f32_e32 v2, 1.0, v2
	v_rcp_f32_e32 v2, v2
	s_nop 0
	v_mul_f32_e32 v1, v2, v1
	v_mul_f32_e32 v0, v1, v0
	v_cvt_pk_bf16_f32 v2, v0, s0
	ds_write_b16 v160, v2 offset:1664
	v_lshlrev_b32_e32 v1, 16, v96
	v_mul_f32_e32 v2, 0xbfb8aa3b, v1
	v_exp_f32_e32 v2, v2
	v_mul_f32_e32 v0, v129, v15
	v_add_f32_e32 v2, 1.0, v2
	v_rcp_f32_e32 v2, v2
	s_nop 0
	v_mul_f32_e32 v1, v2, v1
	v_mul_f32_e32 v0, v1, v0
	v_cvt_pk_bf16_f32 v2, v0, s0
	ds_write_b16 v160, v2 offset:1728
	s_waitcnt lgkmcnt(0)
	ds_read_b128 v[0:3], v162
	ds_read_b128 v[4:7], v162 offset:1024
	s_waitcnt lgkmcnt(1)
	global_store_dwordx4 v[166:167], v[0:3], off
	s_waitcnt lgkmcnt(0)
	global_store_dwordx4 v[168:169], v[4:7], off
	s_barrier
	s_cbranch_scc0 .LBB0_336
	s_branch .LBB0_328
